# PEER pass index permuted so that a workgroup's 64 tokens lie in a GEMM row panel owned by its own XCD (pass = (bid & 7) * 32 + (bid >> 3)); on top of v076
# speedup vs baseline: 1.0017x; 1.0017x over previous
.LBB0_13:
	v_readlane_b32 s0, v254, 16
	s_add_i32 s10, s0, -2
	s_and_b32 s0, s10, 0xff
	s_mul_i32 s0, s0, 37
	s_lshr_b32 s0, s0, 8
	s_sub_i32 s1, s10, s0
	s_bfe_u32 s1, s1, 0x70001
	s_add_i32 s1, s1, s0
	s_bfe_u32 s92, s1, 0x60002
	s_mul_i32 s0, s92, 7
	s_sub_i32 s0, s10, s0
	s_and_b32 s0, s0, 0xff
	v_writelane_b32 v254, s0, 18
	s_cmp_lt_i32 s0, 3
	s_mov_b64 s[0:1], -1
	s_cbranch_scc1 .LBB0_403
	v_readlane_b32 s0, v254, 18
	s_and_b32 s2, 0xffff, s0
	v_writelane_b32 v254, s91, 19
	s_cmp_lt_i32 s2, 4
	s_mov_b64 s[0:1], -1
	v_writelane_b32 v254, s92, 20
	s_cbranch_scc1 .LBB0_346
	s_cmp_lt_i32 s2, 5
	s_cbranch_scc1 .LBB0_207
	s_cmp_lg_u32 s2, 5
	s_cbranch_scc0 .LBB0_161
	v_readlane_b32 s0, v254, 3
	v_readlane_b32 s1, v254, 4
	v_readlane_b32 s2, v254, 5
	v_readlane_b32 s3, v254, 6
	s_mov_b64 s[14:15], s[0:1]
	s_mov_b64 s[0:1], s[2:3]
	s_mov_b32 s57, s61
	v_writelane_b32 v254, s0, 23
	v_mov_b32_e32 v133, v0
	s_nop 0
	v_writelane_b32 v254, s1, 24
	s_nop 0
	v_readlane_b32 s0, v254, 0
	s_mov_b32 s16, s0
	v_readlane_b32 s0, v254, 12
	v_readlane_b32 s1, v254, 13
	s_load_dword s0, s[0:1], 0x0
	s_waitcnt lgkmcnt(0)
	s_cmp_eq_u32 s0, 0x100
	s_cbranch_scc0 .Lpeer_noperm
	s_lshr_b32 s1, s16, 3
	s_and_b32 s16, s16, 7
	s_lshl_b32 s16, s16, 5
	s_or_b32 s16, s16, s1
.Lpeer_noperm:
	s_cmpk_gt_i32 s16, 0xff
	v_writelane_b32 v254, s0, 54
	v_readfirstlane_b32 s0, v133
	s_cbranch_scc1 .LBB0_160
	s_ashr_i32 s2, s0, 6
	v_readlane_b32 s12, v254, 23
	v_readlane_b32 s13, v254, 24
	s_add_u32 s0, s12, 0x8000000
	s_addc_u32 s1, s13, 0
	s_add_u32 s22, s12, 0x4000000
	s_addc_u32 s23, s13, 0
	s_add_u32 s24, s12, 0x21000000
	s_addc_u32 s25, s13, 0
	s_add_u32 s26, s12, 0x21800000
	v_writelane_b32 v254, s0, 27
	s_addc_u32 s27, s13, 0
	v_and_b32_e32 v2, 1, v133
	v_writelane_b32 v254, s1, 28
	s_add_u32 s0, s12, 0x100000
	v_writelane_b32 v254, s0, 29
	s_addc_u32 s0, s13, 0
	v_writelane_b32 v254, s0, 30
	v_and_b32_e32 v176, 63, v133
	v_readlane_b32 s11, v254, 20
	s_lshl_b32 s0, s11, 17
	s_add_u32 s0, s12, s0
	s_addc_u32 s1, s13, 0
	s_add_u32 s28, s0, 0x2a000000
	s_mul_i32 s0, s2, 0x3840
	s_addc_u32 s29, s1, 0
	s_add_i32 s93, s57, s0
	s_lshl_b32 s0, s11, 24
	s_add_u32 s0, s12, s0
	s_addc_u32 s1, s13, 0
	s_lshl_b32 s2, s2, 3
	v_writelane_b32 v254, s2, 58
	s_lshl_b32 s2, s11, 4
	v_writelane_b32 v254, s2, 60
	v_cmp_eq_u32_e64 s[2:3], 0, v2
	v_and_b32_e32 v2, 2, v133
	v_bfe_u32 v1, v133, 4, 2
	v_cmp_eq_u32_e64 s[4:5], 0, v2
	v_bfe_u32 v2, v133, 2, 2
	v_lshlrev_b32_e32 v154, 4, v176
	v_cmp_eq_u32_e64 s[6:7], v1, v2
	v_lshlrev_b32_e32 v2, 2, v133
	v_and_b32_e32 v4, 15, v133
	v_and_b32_e32 v180, 12, v2
	v_lshl_add_u64 v[2:3], s[0:1], 0, v[154:155]
	s_mov_b64 s[8:9], 0x22000000
	v_lshl_add_u64 v[130:131], v[2:3], 0, s[8:9]
	v_cmp_eq_u32_e64 s[18:19], 0, v176
	v_lshlrev_b32_e32 v2, 3, v133
	v_lshlrev_b32_e32 v154, 4, v4
	v_writelane_b32 v254, s18, 21
	v_and_b32_e32 v132, 56, v2
	v_lshl_add_u64 v[2:3], s[0:1], 0, v[154:155]
	s_mov_b64 s[0:1], 0x26000000
	s_cmp_gt_u32 s10, 20
	v_writelane_b32 v254, s19, 22
	v_lshl_add_u64 v[134:135], v[2:3], 0, s[0:1]
	s_cselect_b64 s[0:1], -1, 0
	v_writelane_b32 v254, s0, 25
	v_lshlrev_b32_e32 v177, 2, v176
	v_add_u32_e32 v178, s93, v177
	v_writelane_b32 v254, s1, 26
	s_lshl_b32 s0, s11, 10
	s_addk_i32 s0, 0x400
	v_writelane_b32 v254, s0, 32
	s_add_u32 s0, s12, 0x1c000000
	s_addc_u32 s1, s13, 0
	v_writelane_b32 v254, s0, 62
	s_mov_b32 s96, 0
	v_add_u32_e32 v179, 0x3000, v178
	v_writelane_b32 v254, s1, 63
	s_add_u32 s0, s12, 0x2a200000
	s_addc_u32 s1, s13, 0
	v_writelane_b32 v255, s0, 0
	v_writelane_b32 v254, s14, 56
	v_add_u32_e32 v181, s93, v180
	v_cmp_gt_u32_e64 s[8:9], 4, v176
	v_and_or_b32 v182, v133, 8, 16
	v_lshl_add_u32 v183, v1, 2, s93
	v_writelane_b32 v255, s1, 1
	v_writelane_b32 v254, s15, 57
	s_branch .LBB0_20
